# pool-fold operands (cold first fetch) requested right after the transpose barrier, before silu/adaLN/S5 tables, into registers those steps never touch; fold remapped (128 columns x 16 channels per wor
# speedup vs baseline: 1.0015x; 1.0015x over previous
.Ltr_done:
.LBB0_45:
	s_barrier
	s_waitcnt vmcnt(0)
	s_cmpk_lg_i32 s56, 0x100
	s_cbranch_scc1 .Lpf5_nopre
	v_mbcnt_lo_u32_b32 v224, -1, 0
	v_mbcnt_hi_u32_b32 v224, -1, v224
	v_readlane_b32 s0, v246, 6
	s_lshr_b32 s1, s0, 6
	s_bfe_u32 s9, s0, 0x30003
	s_and_b32 s12, s0, 7
	v_lshrrev_b32_e32 v225, 2, v224
	v_and_b32_e32 v226, 3, v224
	v_lshlrev_b32_e32 v227, 9, v225
	v_lshl_add_u32 v227, v226, 4, v227
	v_readlane_b32 s14, v247, 30
	v_readlane_b32 s15, v247, 31
	s_lshl_b32 s24, s1, 16
	s_lshl_b32 s25, s9, 13
	s_add_i32 s24, s24, s25
	s_lshl_b32 s25, s94, 6
	s_add_i32 s24, s24, s25
	s_add_u32 s14, s14, s24
	s_addc_u32 s15, s15, 0
	v_lshlrev_b32_e32 v228, 4, v226
	v_readlane_b32 s16, v247, 32
	v_readlane_b32 s17, v247, 33
	s_lshl_b32 s24, s1, 9
	s_add_i32 s24, s24, s25
	s_add_u32 s16, s16, s24
	s_addc_u32 s17, s17, 0
	v_readlane_b32 s18, v247, 36
	v_readlane_b32 s19, v247, 37
	s_lshl_b32 s24, s1, 7
	s_lshl_b32 s25, s94, 4
	s_add_i32 s24, s24, s25
	s_lshl_b32 s24, s24, 12
	s_lshl_b32 s25, s12, 9
	s_add_i32 s24, s24, s25
	s_add_u32 s18, s18, s24
	s_addc_u32 s19, s19, 0
	v_lshlrev_b32_e32 v229, 3, v224
	s_nop 3
	global_load_dwordx4 v[216:219], v227, s[14:15]
	global_load_dwordx4 v[220:223], v228, s[16:17]
	global_load_dwordx2 v[184:185], v229, s[18:19]
	s_add_u32 s18, s18, 0x1000
	s_addc_u32 s19, s19, 0
	global_load_dwordx2 v[186:187], v229, s[18:19]
	s_add_u32 s18, s18, 0x1000
	s_addc_u32 s19, s19, 0
	global_load_dwordx2 v[188:189], v229, s[18:19]
	s_add_u32 s18, s18, 0x1000
	s_addc_u32 s19, s19, 0
	global_load_dwordx2 v[190:191], v229, s[18:19]
	s_add_u32 s18, s18, 0x1000
	s_addc_u32 s19, s19, 0
	global_load_dwordx2 v[192:193], v229, s[18:19]
	s_add_u32 s18, s18, 0x1000
	s_addc_u32 s19, s19, 0
	global_load_dwordx2 v[194:195], v229, s[18:19]
	s_add_u32 s18, s18, 0x1000
	s_addc_u32 s19, s19, 0
	global_load_dwordx2 v[196:197], v229, s[18:19]
	s_add_u32 s18, s18, 0x1000
	s_addc_u32 s19, s19, 0
	global_load_dwordx2 v[198:199], v229, s[18:19]
	s_add_u32 s18, s18, 0x1000
	s_addc_u32 s19, s19, 0
	global_load_dwordx2 v[200:201], v229, s[18:19]
	s_add_u32 s18, s18, 0x1000
	s_addc_u32 s19, s19, 0
	global_load_dwordx2 v[202:203], v229, s[18:19]
	s_add_u32 s18, s18, 0x1000
	s_addc_u32 s19, s19, 0
	global_load_dwordx2 v[204:205], v229, s[18:19]
	s_add_u32 s18, s18, 0x1000
	s_addc_u32 s19, s19, 0
	global_load_dwordx2 v[206:207], v229, s[18:19]
	s_add_u32 s18, s18, 0x1000
	s_addc_u32 s19, s19, 0
	global_load_dwordx2 v[208:209], v229, s[18:19]
	s_add_u32 s18, s18, 0x1000
	s_addc_u32 s19, s19, 0
	global_load_dwordx2 v[210:211], v229, s[18:19]
	s_add_u32 s18, s18, 0x1000
	s_addc_u32 s19, s19, 0
	global_load_dwordx2 v[212:213], v229, s[18:19]
	s_add_u32 s18, s18, 0x1000
	s_addc_u32 s19, s19, 0
	global_load_dwordx2 v[214:215], v229, s[18:19]
	s_add_u32 s18, s18, 0x1000
	s_addc_u32 s19, s19, 0
.Lpf5_nopre:
	s_and_b32 s0, s93, 0xffffffc0
	v_readlane_b32 s1, v246, 6
	s_cmpk_gt_i32 s1, 0xbf
	v_add_u32_e32 v160, s0, v163
	s_nop 0
	v_readlane_b32 s1, v247, 21
	v_readlane_b32 s0, v247, 20
	s_nop 0
	v_readlane_b32 s13, v247, 23
	v_readlane_b32 s12, v247, 22
	s_nop 0
	v_readlane_b32 s19, v247, 5
	v_readlane_b32 s18, v247, 4
	s_nop 0
	v_readlane_b32 s15, v247, 15
	v_readlane_b32 s14, v247, 14
	s_cbranch_scc1 .LBB0_55
	s_movk_i32 s9, 0x1400
	v_cmp_gt_i32_e32 vcc, s9, v160
	s_and_saveexec_b64 s[16:17], vcc
	s_cbranch_execz .LBB0_49
	s_lshl_b32 s9, s94, 8
	v_ashrrev_i32_e32 v161, 31, v160
	s_add_i32 s9, s9, 0
	s_movk_i32 s20, 0xc000
	v_lshl_add_u64 v[0:1], v[160:161], 2, s[18:19]
	v_lshl_add_u32 v4, v163, 2, s9
	s_mov_b64 s[18:19], 0
	s_movk_i32 s9, 0x1000
	v_mov_b32_e32 v3, 0
	s_mov_b32 s21, -1
	s_mov_b64 s[22:23], 0x800
	s_movk_i32 s24, 0x11ff
	v_mov_b32_e32 v2, v160
	s_mov_b64 s[18:19], 0x1000
	v_lshlrev_b32_e32 v8, 2, v2
	global_load_dword v20, v[0:1], off
	global_load_dword v21, v[0:1], off offset:2048
	v_lshl_add_u64 v[6:7], v[0:1], 0, s[18:19]
	global_load_dword v22, v[6:7], off
	global_load_dword v23, v[6:7], off offset:2048
	v_lshl_add_u64 v[6:7], v[6:7], 0, s[18:19]
	global_load_dword v24, v[6:7], off
	global_load_dword v25, v[6:7], off offset:2048
	v_lshl_add_u64 v[6:7], v[6:7], 0, s[18:19]
	global_load_dword v26, v[6:7], off
	global_load_dword v27, v[6:7], off offset:2048
	global_load_dword v28, v8, s[14:15]
	global_load_dword v29, v8, s[14:15] offset:2048
	s_waitcnt vmcnt(0) lgkmcnt(0)
	v_mul_f32_e32 v30, 0xbfb8aa3b, v20
	v_exp_f32_e32 v30, v30
	s_nop 0
	v_add_f32_e32 v30, 1.0, v30
	v_div_scale_f32 v31, s[26:27], v30, v30, 1.0
	v_rcp_f32_e32 v32, v31
	v_div_scale_f32 v33, vcc, 1.0, v30, 1.0
	v_fma_f32 v34, -v31, v32, 1.0
	v_fmac_f32_e32 v32, v34, v32
	v_mul_f32_e32 v34, v33, v32
	v_fma_f32 v35, -v31, v34, v33
	v_fmac_f32_e32 v34, v35, v32
	v_fma_f32 v31, -v31, v34, v33
	v_div_fmas_f32 v31, v31, v32, v34
	v_div_fixup_f32 v30, v31, v30, 1.0
	v_mul_f32_e32 v20, v20, v30
	ds_write_b32 v4, v20
	v_mul_f32_e32 v38, 0xbfb8aa3b, v21
	v_exp_f32_e32 v38, v38
	s_nop 0
	v_add_f32_e32 v38, 1.0, v38
	v_div_scale_f32 v39, s[26:27], v38, v38, 1.0
	v_rcp_f32_e32 v40, v39
	v_div_scale_f32 v41, vcc, 1.0, v38, 1.0
	v_fma_f32 v42, -v39, v40, 1.0
	v_fmac_f32_e32 v40, v42, v40
	v_mul_f32_e32 v42, v41, v40
	v_fma_f32 v43, -v39, v42, v41
	v_fmac_f32_e32 v42, v43, v40
	v_fma_f32 v39, -v39, v42, v41
	v_div_fmas_f32 v39, v39, v40, v42
	v_div_fixup_f32 v38, v39, v38, 1.0
	v_mul_f32_e32 v21, v21, v38
	ds_write_b32 v4, v21 offset:2048
	v_mul_f32_e32 v46, 0xbfb8aa3b, v22
	v_exp_f32_e32 v46, v46
	s_nop 0
	v_add_f32_e32 v46, 1.0, v46
	v_div_scale_f32 v47, s[26:27], v46, v46, 1.0
	v_rcp_f32_e32 v48, v47
	v_div_scale_f32 v49, vcc, 1.0, v46, 1.0
	v_fma_f32 v50, -v47, v48, 1.0
	v_fmac_f32_e32 v48, v50, v48
	v_mul_f32_e32 v50, v49, v48
	v_fma_f32 v51, -v47, v50, v49
	v_fmac_f32_e32 v50, v51, v48
	v_fma_f32 v47, -v47, v50, v49
	v_div_fmas_f32 v47, v47, v48, v50
	v_div_fixup_f32 v46, v47, v46, 1.0
	v_mul_f32_e32 v22, v22, v46
	ds_write_b32 v4, v22 offset:4096
	v_mul_f32_e32 v54, 0xbfb8aa3b, v23
	v_exp_f32_e32 v54, v54
	s_nop 0
	v_add_f32_e32 v54, 1.0, v54
	v_div_scale_f32 v55, s[26:27], v54, v54, 1.0
	v_rcp_f32_e32 v56, v55
	v_div_scale_f32 v57, vcc, 1.0, v54, 1.0
	v_fma_f32 v58, -v55, v56, 1.0
	v_fmac_f32_e32 v56, v58, v56
	v_mul_f32_e32 v58, v57, v56
	v_fma_f32 v59, -v55, v58, v57
	v_fmac_f32_e32 v58, v59, v56
	v_fma_f32 v55, -v55, v58, v57
	v_div_fmas_f32 v55, v55, v56, v58
	v_div_fixup_f32 v54, v55, v54, 1.0
	v_mul_f32_e32 v23, v23, v54
	ds_write_b32 v4, v23 offset:6144
	v_mul_f32_e32 v62, 0xbfb8aa3b, v24
	v_exp_f32_e32 v62, v62
	s_nop 0
	v_add_f32_e32 v62, 1.0, v62
	v_div_scale_f32 v63, s[26:27], v62, v62, 1.0
	v_rcp_f32_e32 v64, v63
	v_div_scale_f32 v65, vcc, 1.0, v62, 1.0
	v_fma_f32 v66, -v63, v64, 1.0
	v_fmac_f32_e32 v64, v66, v64
	v_mul_f32_e32 v66, v65, v64
	v_fma_f32 v67, -v63, v66, v65
	v_fmac_f32_e32 v66, v67, v64
	v_fma_f32 v63, -v63, v66, v65
	v_div_fmas_f32 v63, v63, v64, v66
	v_div_fixup_f32 v62, v63, v62, 1.0
	v_mul_f32_e32 v24, v24, v62
	ds_write_b32 v4, v24 offset:8192
	v_mul_f32_e32 v70, 0xbfb8aa3b, v25
	v_exp_f32_e32 v70, v70
	s_nop 0
	v_add_f32_e32 v70, 1.0, v70
	v_div_scale_f32 v71, s[26:27], v70, v70, 1.0
	v_rcp_f32_e32 v72, v71
	v_div_scale_f32 v73, vcc, 1.0, v70, 1.0
	v_fma_f32 v74, -v71, v72, 1.0
	v_fmac_f32_e32 v72, v74, v72
	v_mul_f32_e32 v74, v73, v72
	v_fma_f32 v75, -v71, v74, v73
	v_fmac_f32_e32 v74, v75, v72
	v_fma_f32 v71, -v71, v74, v73
	v_div_fmas_f32 v71, v71, v72, v74
	v_div_fixup_f32 v70, v71, v70, 1.0
	v_mul_f32_e32 v25, v25, v70
	ds_write_b32 v4, v25 offset:10240
	v_mul_f32_e32 v78, 0xbfb8aa3b, v26
	v_exp_f32_e32 v78, v78
	s_nop 0
	v_add_f32_e32 v78, 1.0, v78
	v_div_scale_f32 v79, s[26:27], v78, v78, 1.0
	v_rcp_f32_e32 v80, v79
	v_div_scale_f32 v81, vcc, 1.0, v78, 1.0
	v_fma_f32 v82, -v79, v80, 1.0
	v_fmac_f32_e32 v80, v82, v80
	v_mul_f32_e32 v82, v81, v80
	v_fma_f32 v83, -v79, v82, v81
	v_fmac_f32_e32 v82, v83, v80
	v_fma_f32 v79, -v79, v82, v81
	v_div_fmas_f32 v79, v79, v80, v82
	v_div_fixup_f32 v78, v79, v78, 1.0
	v_mul_f32_e32 v26, v26, v78
	ds_write_b32 v4, v26 offset:12288
	v_mul_f32_e32 v86, 0xbfb8aa3b, v27
	v_exp_f32_e32 v86, v86
	s_nop 0
	v_add_f32_e32 v86, 1.0, v86
	v_div_scale_f32 v87, s[26:27], v86, v86, 1.0
	v_rcp_f32_e32 v88, v87
	v_div_scale_f32 v89, vcc, 1.0, v86, 1.0
	v_fma_f32 v90, -v87, v88, 1.0
	v_fmac_f32_e32 v88, v90, v88
	v_mul_f32_e32 v90, v89, v88
	v_fma_f32 v91, -v87, v90, v89
	v_fmac_f32_e32 v90, v91, v88
	v_fma_f32 v87, -v87, v90, v89
	v_div_fmas_f32 v87, v87, v88, v90
	v_div_fixup_f32 v86, v87, v86, 1.0
	v_mul_f32_e32 v27, v27, v86
	ds_write_b32 v4, v27 offset:14336
	v_mul_f32_e32 v94, 0xbfb8aa3b, v28
	v_exp_f32_e32 v94, v94
	s_nop 0
	v_add_f32_e32 v94, 1.0, v94
	v_div_scale_f32 v95, s[26:27], v94, v94, 1.0
	v_rcp_f32_e32 v96, v95
	v_div_scale_f32 v97, vcc, 1.0, v94, 1.0
	v_fma_f32 v98, -v95, v96, 1.0
	v_fmac_f32_e32 v96, v98, v96
	v_mul_f32_e32 v98, v97, v96
	v_fma_f32 v99, -v95, v98, v97
	v_fmac_f32_e32 v98, v99, v96
	v_fma_f32 v95, -v95, v98, v97
	v_div_fmas_f32 v95, v95, v96, v98
	v_div_fixup_f32 v94, v95, v94, 1.0
	v_mul_f32_e32 v28, v28, v94
	ds_write_b32 v4, v28 offset:16384
	v_mul_f32_e32 v102, 0xbfb8aa3b, v29
	v_exp_f32_e32 v102, v102
	s_nop 0
	v_add_f32_e32 v102, 1.0, v102
	v_div_scale_f32 v103, s[26:27], v102, v102, 1.0
	v_rcp_f32_e32 v104, v103
	v_div_scale_f32 v105, vcc, 1.0, v102, 1.0
	v_fma_f32 v106, -v103, v104, 1.0
	v_fmac_f32_e32 v104, v106, v104
	v_mul_f32_e32 v106, v105, v104
	v_fma_f32 v107, -v103, v106, v105
	v_fmac_f32_e32 v106, v107, v104
	v_fma_f32 v103, -v103, v106, v105
	v_div_fmas_f32 v103, v103, v104, v106
	v_div_fixup_f32 v102, v103, v102, 1.0
	v_mul_f32_e32 v29, v29, v102
	ds_write_b32 v4, v29 offset:18432

.LBB0_65:
	s_or_b64 exec, exec, s[20:21]
	v_mov_b32_e32 v3, 0
	s_mov_b32 s0, 0x20000
	v_cmp_gt_i32_e32 vcc, s0, v0
	s_waitcnt vmcnt(1)
	v_readlane_b32 s13, v247, 31
	v_readlane_b32 s12, v247, 30
	s_waitcnt vmcnt(0)
	v_readlane_b32 s15, v247, 33
	v_readlane_b32 s14, v247, 32
	s_and_saveexec_b64 s[16:17], vcc
	s_cbranch_execz .LBB0_70
	s_cmpk_lg_i32 s56, 0x100
	s_cbranch_scc1 .Lpf5_generic
	v_mbcnt_lo_u32_b32 v1, -1, 0
	v_mbcnt_hi_u32_b32 v1, -1, v1
	v_readlane_b32 s0, v246, 6
	s_lshr_b32 s1, s0, 6
	s_bfe_u32 s9, s0, 0x30003
	s_and_b32 s18, s0, 7
	v_lshrrev_b32_e32 v2, 2, v1
	v_and_b32_e32 v3, 3, v1
	v_lshlrev_b32_e32 v5, 4, v3
	s_waitcnt vmcnt(0)
	s_lshl_b32 s23, s94, 14
	v_lshlrev_b32_e32 v6, 8, v3
	v_lshl_add_u32 v6, v2, 2, v6
	v_add_u32_e32 v6, s23, v6
	ds_write_b32 v6, v216
	ds_write_b32 v6, v217 offset:64
	ds_write_b32 v6, v218 offset:128
	ds_write_b32 v6, v219 offset:192
	v_add_u32_e32 v7, s23, v5
	ds_write_b128 v7, v[220:223] offset:1024
	v_mov_b32_e32 v63, s23
	s_waitcnt lgkmcnt(0)
	v_mov_b32_e32 v10, 0
	v_mov_b32_e32 v11, 0
	v_mov_b32_e32 v12, 0
	v_mov_b32_e32 v13, 0
	v_mov_b32_e32 v14, 0
	v_mov_b32_e32 v15, 0
	v_mov_b32_e32 v16, 0
	v_mov_b32_e32 v17, 0
	v_mov_b32_e32 v18, 0
	v_mov_b32_e32 v19, 0
	v_mov_b32_e32 v20, 0
	v_mov_b32_e32 v21, 0
	v_mov_b32_e32 v22, 0
	v_mov_b32_e32 v23, 0
	v_mov_b32_e32 v24, 0
	v_mov_b32_e32 v25, 0
	v_mov_b32_e32 v26, 0
	v_mov_b32_e32 v27, 0
	v_mov_b32_e32 v28, 0
	v_mov_b32_e32 v29, 0
	v_mov_b32_e32 v30, 0
	v_mov_b32_e32 v31, 0
	v_mov_b32_e32 v32, 0
	v_mov_b32_e32 v33, 0
	v_mov_b32_e32 v34, 0
	v_mov_b32_e32 v35, 0
	v_mov_b32_e32 v36, 0
	v_mov_b32_e32 v37, 0
	v_mov_b32_e32 v38, 0
	v_mov_b32_e32 v39, 0
	v_mov_b32_e32 v40, 0
	v_mov_b32_e32 v41, 0
	ds_read_b128 v[104:107], v63 offset:0
	ds_read_b128 v[108:111], v63 offset:16
	ds_read_b128 v[112:115], v63 offset:32
	ds_read_b128 v[116:119], v63 offset:48
	ds_read_b128 v[120:123], v63 offset:64
	ds_read_b128 v[124:127], v63 offset:80
	ds_read_b128 v[128:131], v63 offset:96
	ds_read_b128 v[132:135], v63 offset:112
	ds_read_b128 v[136:139], v63 offset:128
	ds_read_b128 v[140:143], v63 offset:144
	ds_read_b128 v[144:147], v63 offset:160
	ds_read_b128 v[148:151], v63 offset:176
	ds_read_b128 v[152:155], v63 offset:192
	ds_read_b128 v[156:159], v63 offset:208
	ds_read_b128 v[160:163], v63 offset:224
	ds_read_b128 v[164:167], v63 offset:240
	ds_read_b128 v[100:103], v63 offset:1024
	s_waitcnt lgkmcnt(0)
	v_mul_f32_e32 v232, v100, v184
	v_mul_f32_e32 v233, v100, v185
	v_fmac_f32_e32 v10, v104, v232
	v_fmac_f32_e32 v26, v104, v233
	v_fmac_f32_e32 v11, v105, v232
	v_fmac_f32_e32 v27, v105, v233
	v_fmac_f32_e32 v12, v106, v232
	v_fmac_f32_e32 v28, v106, v233
	v_fmac_f32_e32 v13, v107, v232
	v_fmac_f32_e32 v29, v107, v233
	v_fmac_f32_e32 v14, v108, v232
	v_fmac_f32_e32 v30, v108, v233
	v_fmac_f32_e32 v15, v109, v232
	v_fmac_f32_e32 v31, v109, v233
	v_fmac_f32_e32 v16, v110, v232
	v_fmac_f32_e32 v32, v110, v233
	v_fmac_f32_e32 v17, v111, v232
	v_fmac_f32_e32 v33, v111, v233
	v_fmac_f32_e32 v18, v112, v232
	v_fmac_f32_e32 v34, v112, v233
	v_fmac_f32_e32 v19, v113, v232
	v_fmac_f32_e32 v35, v113, v233
	v_fmac_f32_e32 v20, v114, v232
	v_fmac_f32_e32 v36, v114, v233
	v_fmac_f32_e32 v21, v115, v232
	v_fmac_f32_e32 v37, v115, v233
	v_fmac_f32_e32 v22, v116, v232
	v_fmac_f32_e32 v38, v116, v233
	v_fmac_f32_e32 v23, v117, v232
	v_fmac_f32_e32 v39, v117, v233
	v_fmac_f32_e32 v24, v118, v232
	v_fmac_f32_e32 v40, v118, v233
	v_fmac_f32_e32 v25, v119, v232
	v_fmac_f32_e32 v41, v119, v233
	v_mul_f32_e32 v232, v101, v186
	v_mul_f32_e32 v233, v101, v187
	v_fmac_f32_e32 v10, v120, v232
	v_fmac_f32_e32 v26, v120, v233
	v_fmac_f32_e32 v11, v121, v232
	v_fmac_f32_e32 v27, v121, v233
	v_fmac_f32_e32 v12, v122, v232
	v_fmac_f32_e32 v28, v122, v233
	v_fmac_f32_e32 v13, v123, v232
	v_fmac_f32_e32 v29, v123, v233
	v_fmac_f32_e32 v14, v124, v232
	v_fmac_f32_e32 v30, v124, v233
	v_fmac_f32_e32 v15, v125, v232
	v_fmac_f32_e32 v31, v125, v233
	v_fmac_f32_e32 v16, v126, v232
	v_fmac_f32_e32 v32, v126, v233
	v_fmac_f32_e32 v17, v127, v232
	v_fmac_f32_e32 v33, v127, v233
	v_fmac_f32_e32 v18, v128, v232
	v_fmac_f32_e32 v34, v128, v233
	v_fmac_f32_e32 v19, v129, v232
	v_fmac_f32_e32 v35, v129, v233
	v_fmac_f32_e32 v20, v130, v232
	v_fmac_f32_e32 v36, v130, v233
	v_fmac_f32_e32 v21, v131, v232
	v_fmac_f32_e32 v37, v131, v233
	v_fmac_f32_e32 v22, v132, v232
	v_fmac_f32_e32 v38, v132, v233
	v_fmac_f32_e32 v23, v133, v232
	v_fmac_f32_e32 v39, v133, v233
	v_fmac_f32_e32 v24, v134, v232
	v_fmac_f32_e32 v40, v134, v233
	v_fmac_f32_e32 v25, v135, v232
	v_fmac_f32_e32 v41, v135, v233
	v_mul_f32_e32 v232, v102, v188
	v_mul_f32_e32 v233, v102, v189
	v_fmac_f32_e32 v10, v136, v232
	v_fmac_f32_e32 v26, v136, v233
	v_fmac_f32_e32 v11, v137, v232
	v_fmac_f32_e32 v27, v137, v233
	v_fmac_f32_e32 v12, v138, v232
	v_fmac_f32_e32 v28, v138, v233
	v_fmac_f32_e32 v13, v139, v232
	v_fmac_f32_e32 v29, v139, v233
	v_fmac_f32_e32 v14, v140, v232
	v_fmac_f32_e32 v30, v140, v233
	v_fmac_f32_e32 v15, v141, v232
	v_fmac_f32_e32 v31, v141, v233
	v_fmac_f32_e32 v16, v142, v232
	v_fmac_f32_e32 v32, v142, v233
	v_fmac_f32_e32 v17, v143, v232
	v_fmac_f32_e32 v33, v143, v233
	v_fmac_f32_e32 v18, v144, v232
	v_fmac_f32_e32 v34, v144, v233
	v_fmac_f32_e32 v19, v145, v232
	v_fmac_f32_e32 v35, v145, v233
	v_fmac_f32_e32 v20, v146, v232
	v_fmac_f32_e32 v36, v146, v233
	v_fmac_f32_e32 v21, v147, v232
	v_fmac_f32_e32 v37, v147, v233
	v_fmac_f32_e32 v22, v148, v232
	v_fmac_f32_e32 v38, v148, v233
	v_fmac_f32_e32 v23, v149, v232
	v_fmac_f32_e32 v39, v149, v233
	v_fmac_f32_e32 v24, v150, v232
	v_fmac_f32_e32 v40, v150, v233
	v_fmac_f32_e32 v25, v151, v232
	v_fmac_f32_e32 v41, v151, v233
	v_mul_f32_e32 v232, v103, v190
	v_mul_f32_e32 v233, v103, v191
	v_fmac_f32_e32 v10, v152, v232
	v_fmac_f32_e32 v26, v152, v233
	v_fmac_f32_e32 v11, v153, v232
	v_fmac_f32_e32 v27, v153, v233
	v_fmac_f32_e32 v12, v154, v232
	v_fmac_f32_e32 v28, v154, v233
	v_fmac_f32_e32 v13, v155, v232
	v_fmac_f32_e32 v29, v155, v233
	v_fmac_f32_e32 v14, v156, v232
	v_fmac_f32_e32 v30, v156, v233
	v_fmac_f32_e32 v15, v157, v232
	v_fmac_f32_e32 v31, v157, v233
	v_fmac_f32_e32 v16, v158, v232
	v_fmac_f32_e32 v32, v158, v233
	v_fmac_f32_e32 v17, v159, v232
	v_fmac_f32_e32 v33, v159, v233
	v_fmac_f32_e32 v18, v160, v232
	v_fmac_f32_e32 v34, v160, v233
	v_fmac_f32_e32 v19, v161, v232
	v_fmac_f32_e32 v35, v161, v233
	v_fmac_f32_e32 v20, v162, v232
	v_fmac_f32_e32 v36, v162, v233
	v_fmac_f32_e32 v21, v163, v232
	v_fmac_f32_e32 v37, v163, v233
	v_fmac_f32_e32 v22, v164, v232
	v_fmac_f32_e32 v38, v164, v233
	v_fmac_f32_e32 v23, v165, v232
	v_fmac_f32_e32 v39, v165, v233
	v_fmac_f32_e32 v24, v166, v232
	v_fmac_f32_e32 v40, v166, v233
	v_fmac_f32_e32 v25, v167, v232
	v_fmac_f32_e32 v41, v167, v233
	ds_read_b128 v[104:107], v63 offset:256
	ds_read_b128 v[108:111], v63 offset:272
	ds_read_b128 v[112:115], v63 offset:288
	ds_read_b128 v[116:119], v63 offset:304
	ds_read_b128 v[120:123], v63 offset:320
	ds_read_b128 v[124:127], v63 offset:336
	ds_read_b128 v[128:131], v63 offset:352
	ds_read_b128 v[132:135], v63 offset:368
	ds_read_b128 v[136:139], v63 offset:384
	ds_read_b128 v[140:143], v63 offset:400
	ds_read_b128 v[144:147], v63 offset:416
	ds_read_b128 v[148:151], v63 offset:432
	ds_read_b128 v[152:155], v63 offset:448
	ds_read_b128 v[156:159], v63 offset:464
	ds_read_b128 v[160:163], v63 offset:480
	ds_read_b128 v[164:167], v63 offset:496
	ds_read_b128 v[100:103], v63 offset:1040
	s_waitcnt lgkmcnt(0)
	v_mul_f32_e32 v232, v100, v192
	v_mul_f32_e32 v233, v100, v193
	v_fmac_f32_e32 v10, v104, v232
	v_fmac_f32_e32 v26, v104, v233
	v_fmac_f32_e32 v11, v105, v232
	v_fmac_f32_e32 v27, v105, v233
	v_fmac_f32_e32 v12, v106, v232
	v_fmac_f32_e32 v28, v106, v233
	v_fmac_f32_e32 v13, v107, v232
	v_fmac_f32_e32 v29, v107, v233
	v_fmac_f32_e32 v14, v108, v232
	v_fmac_f32_e32 v30, v108, v233
	v_fmac_f32_e32 v15, v109, v232
	v_fmac_f32_e32 v31, v109, v233
	v_fmac_f32_e32 v16, v110, v232
	v_fmac_f32_e32 v32, v110, v233
	v_fmac_f32_e32 v17, v111, v232
	v_fmac_f32_e32 v33, v111, v233
	v_fmac_f32_e32 v18, v112, v232
	v_fmac_f32_e32 v34, v112, v233
	v_fmac_f32_e32 v19, v113, v232
	v_fmac_f32_e32 v35, v113, v233
	v_fmac_f32_e32 v20, v114, v232
	v_fmac_f32_e32 v36, v114, v233
	v_fmac_f32_e32 v21, v115, v232
	v_fmac_f32_e32 v37, v115, v233
	v_fmac_f32_e32 v22, v116, v232
	v_fmac_f32_e32 v38, v116, v233
	v_fmac_f32_e32 v23, v117, v232
	v_fmac_f32_e32 v39, v117, v233
	v_fmac_f32_e32 v24, v118, v232
	v_fmac_f32_e32 v40, v118, v233
	v_fmac_f32_e32 v25, v119, v232
	v_fmac_f32_e32 v41, v119, v233
	v_mul_f32_e32 v232, v101, v194
	v_mul_f32_e32 v233, v101, v195
	v_fmac_f32_e32 v10, v120, v232
	v_fmac_f32_e32 v26, v120, v233
	v_fmac_f32_e32 v11, v121, v232
	v_fmac_f32_e32 v27, v121, v233
	v_fmac_f32_e32 v12, v122, v232
	v_fmac_f32_e32 v28, v122, v233
	v_fmac_f32_e32 v13, v123, v232
	v_fmac_f32_e32 v29, v123, v233
	v_fmac_f32_e32 v14, v124, v232
	v_fmac_f32_e32 v30, v124, v233
	v_fmac_f32_e32 v15, v125, v232
	v_fmac_f32_e32 v31, v125, v233
	v_fmac_f32_e32 v16, v126, v232
	v_fmac_f32_e32 v32, v126, v233
	v_fmac_f32_e32 v17, v127, v232
	v_fmac_f32_e32 v33, v127, v233
	v_fmac_f32_e32 v18, v128, v232
	v_fmac_f32_e32 v34, v128, v233
	v_fmac_f32_e32 v19, v129, v232
	v_fmac_f32_e32 v35, v129, v233
	v_fmac_f32_e32 v20, v130, v232
	v_fmac_f32_e32 v36, v130, v233
	v_fmac_f32_e32 v21, v131, v232
	v_fmac_f32_e32 v37, v131, v233
	v_fmac_f32_e32 v22, v132, v232
	v_fmac_f32_e32 v38, v132, v233
	v_fmac_f32_e32 v23, v133, v232
	v_fmac_f32_e32 v39, v133, v233
	v_fmac_f32_e32 v24, v134, v232
	v_fmac_f32_e32 v40, v134, v233
	v_fmac_f32_e32 v25, v135, v232
	v_fmac_f32_e32 v41, v135, v233
	v_mul_f32_e32 v232, v102, v196
	v_mul_f32_e32 v233, v102, v197
	v_fmac_f32_e32 v10, v136, v232
	v_fmac_f32_e32 v26, v136, v233
	v_fmac_f32_e32 v11, v137, v232
	v_fmac_f32_e32 v27, v137, v233
	v_fmac_f32_e32 v12, v138, v232
	v_fmac_f32_e32 v28, v138, v233
	v_fmac_f32_e32 v13, v139, v232
	v_fmac_f32_e32 v29, v139, v233
	v_fmac_f32_e32 v14, v140, v232
	v_fmac_f32_e32 v30, v140, v233
	v_fmac_f32_e32 v15, v141, v232
	v_fmac_f32_e32 v31, v141, v233
	v_fmac_f32_e32 v16, v142, v232
	v_fmac_f32_e32 v32, v142, v233
	v_fmac_f32_e32 v17, v143, v232
	v_fmac_f32_e32 v33, v143, v233
	v_fmac_f32_e32 v18, v144, v232
	v_fmac_f32_e32 v34, v144, v233
	v_fmac_f32_e32 v19, v145, v232
	v_fmac_f32_e32 v35, v145, v233
	v_fmac_f32_e32 v20, v146, v232
	v_fmac_f32_e32 v36, v146, v233
	v_fmac_f32_e32 v21, v147, v232
	v_fmac_f32_e32 v37, v147, v233
	v_fmac_f32_e32 v22, v148, v232
	v_fmac_f32_e32 v38, v148, v233
	v_fmac_f32_e32 v23, v149, v232
	v_fmac_f32_e32 v39, v149, v233
	v_fmac_f32_e32 v24, v150, v232
	v_fmac_f32_e32 v40, v150, v233
	v_fmac_f32_e32 v25, v151, v232
	v_fmac_f32_e32 v41, v151, v233
	v_mul_f32_e32 v232, v103, v198
	v_mul_f32_e32 v233, v103, v199
	v_fmac_f32_e32 v10, v152, v232
	v_fmac_f32_e32 v26, v152, v233
	v_fmac_f32_e32 v11, v153, v232
	v_fmac_f32_e32 v27, v153, v233
	v_fmac_f32_e32 v12, v154, v232
	v_fmac_f32_e32 v28, v154, v233
	v_fmac_f32_e32 v13, v155, v232
	v_fmac_f32_e32 v29, v155, v233
	v_fmac_f32_e32 v14, v156, v232
	v_fmac_f32_e32 v30, v156, v233
	v_fmac_f32_e32 v15, v157, v232
	v_fmac_f32_e32 v31, v157, v233
	v_fmac_f32_e32 v16, v158, v232
	v_fmac_f32_e32 v32, v158, v233
	v_fmac_f32_e32 v17, v159, v232
	v_fmac_f32_e32 v33, v159, v233
	v_fmac_f32_e32 v18, v160, v232
	v_fmac_f32_e32 v34, v160, v233
	v_fmac_f32_e32 v19, v161, v232
	v_fmac_f32_e32 v35, v161, v233
	v_fmac_f32_e32 v20, v162, v232
	v_fmac_f32_e32 v36, v162, v233
	v_fmac_f32_e32 v21, v163, v232
	v_fmac_f32_e32 v37, v163, v233
	v_fmac_f32_e32 v22, v164, v232
	v_fmac_f32_e32 v38, v164, v233
	v_fmac_f32_e32 v23, v165, v232
	v_fmac_f32_e32 v39, v165, v233
	v_fmac_f32_e32 v24, v166, v232
	v_fmac_f32_e32 v40, v166, v233
	v_fmac_f32_e32 v25, v167, v232
	v_fmac_f32_e32 v41, v167, v233
	ds_read_b128 v[104:107], v63 offset:512
	ds_read_b128 v[108:111], v63 offset:528
	ds_read_b128 v[112:115], v63 offset:544
	ds_read_b128 v[116:119], v63 offset:560
	ds_read_b128 v[120:123], v63 offset:576
	ds_read_b128 v[124:127], v63 offset:592
	ds_read_b128 v[128:131], v63 offset:608
	ds_read_b128 v[132:135], v63 offset:624
	ds_read_b128 v[136:139], v63 offset:640
	ds_read_b128 v[140:143], v63 offset:656
	ds_read_b128 v[144:147], v63 offset:672
	ds_read_b128 v[148:151], v63 offset:688
	ds_read_b128 v[152:155], v63 offset:704
	ds_read_b128 v[156:159], v63 offset:720
	ds_read_b128 v[160:163], v63 offset:736
	ds_read_b128 v[164:167], v63 offset:752
	ds_read_b128 v[100:103], v63 offset:1056
	s_waitcnt lgkmcnt(0)
	v_mul_f32_e32 v232, v100, v200
	v_mul_f32_e32 v233, v100, v201
	v_fmac_f32_e32 v10, v104, v232
	v_fmac_f32_e32 v26, v104, v233
	v_fmac_f32_e32 v11, v105, v232
	v_fmac_f32_e32 v27, v105, v233
	v_fmac_f32_e32 v12, v106, v232
	v_fmac_f32_e32 v28, v106, v233
	v_fmac_f32_e32 v13, v107, v232
	v_fmac_f32_e32 v29, v107, v233
	v_fmac_f32_e32 v14, v108, v232
	v_fmac_f32_e32 v30, v108, v233
	v_fmac_f32_e32 v15, v109, v232
	v_fmac_f32_e32 v31, v109, v233
	v_fmac_f32_e32 v16, v110, v232
	v_fmac_f32_e32 v32, v110, v233
	v_fmac_f32_e32 v17, v111, v232
	v_fmac_f32_e32 v33, v111, v233
	v_fmac_f32_e32 v18, v112, v232
	v_fmac_f32_e32 v34, v112, v233
	v_fmac_f32_e32 v19, v113, v232
	v_fmac_f32_e32 v35, v113, v233
	v_fmac_f32_e32 v20, v114, v232
	v_fmac_f32_e32 v36, v114, v233
	v_fmac_f32_e32 v21, v115, v232
	v_fmac_f32_e32 v37, v115, v233
	v_fmac_f32_e32 v22, v116, v232
	v_fmac_f32_e32 v38, v116, v233
	v_fmac_f32_e32 v23, v117, v232
	v_fmac_f32_e32 v39, v117, v233
	v_fmac_f32_e32 v24, v118, v232
	v_fmac_f32_e32 v40, v118, v233
	v_fmac_f32_e32 v25, v119, v232
	v_fmac_f32_e32 v41, v119, v233
	v_mul_f32_e32 v232, v101, v202
	v_mul_f32_e32 v233, v101, v203
	v_fmac_f32_e32 v10, v120, v232
	v_fmac_f32_e32 v26, v120, v233
	v_fmac_f32_e32 v11, v121, v232
	v_fmac_f32_e32 v27, v121, v233
	v_fmac_f32_e32 v12, v122, v232
	v_fmac_f32_e32 v28, v122, v233
	v_fmac_f32_e32 v13, v123, v232
	v_fmac_f32_e32 v29, v123, v233
	v_fmac_f32_e32 v14, v124, v232
	v_fmac_f32_e32 v30, v124, v233
	v_fmac_f32_e32 v15, v125, v232
	v_fmac_f32_e32 v31, v125, v233
	v_fmac_f32_e32 v16, v126, v232
	v_fmac_f32_e32 v32, v126, v233
	v_fmac_f32_e32 v17, v127, v232
	v_fmac_f32_e32 v33, v127, v233
	v_fmac_f32_e32 v18, v128, v232
	v_fmac_f32_e32 v34, v128, v233
	v_fmac_f32_e32 v19, v129, v232
	v_fmac_f32_e32 v35, v129, v233
	v_fmac_f32_e32 v20, v130, v232
	v_fmac_f32_e32 v36, v130, v233
	v_fmac_f32_e32 v21, v131, v232
	v_fmac_f32_e32 v37, v131, v233
	v_fmac_f32_e32 v22, v132, v232
	v_fmac_f32_e32 v38, v132, v233
	v_fmac_f32_e32 v23, v133, v232
	v_fmac_f32_e32 v39, v133, v233
	v_fmac_f32_e32 v24, v134, v232
	v_fmac_f32_e32 v40, v134, v233
	v_fmac_f32_e32 v25, v135, v232
	v_fmac_f32_e32 v41, v135, v233
	v_mul_f32_e32 v232, v102, v204
	v_mul_f32_e32 v233, v102, v205
	v_fmac_f32_e32 v10, v136, v232
	v_fmac_f32_e32 v26, v136, v233
	v_fmac_f32_e32 v11, v137, v232
	v_fmac_f32_e32 v27, v137, v233
	v_fmac_f32_e32 v12, v138, v232
	v_fmac_f32_e32 v28, v138, v233
	v_fmac_f32_e32 v13, v139, v232
	v_fmac_f32_e32 v29, v139, v233
	v_fmac_f32_e32 v14, v140, v232
	v_fmac_f32_e32 v30, v140, v233
	v_fmac_f32_e32 v15, v141, v232
	v_fmac_f32_e32 v31, v141, v233
	v_fmac_f32_e32 v16, v142, v232
	v_fmac_f32_e32 v32, v142, v233
	v_fmac_f32_e32 v17, v143, v232
	v_fmac_f32_e32 v33, v143, v233
	v_fmac_f32_e32 v18, v144, v232
	v_fmac_f32_e32 v34, v144, v233
	v_fmac_f32_e32 v19, v145, v232
	v_fmac_f32_e32 v35, v145, v233
	v_fmac_f32_e32 v20, v146, v232
	v_fmac_f32_e32 v36, v146, v233
	v_fmac_f32_e32 v21, v147, v232
	v_fmac_f32_e32 v37, v147, v233
	v_fmac_f32_e32 v22, v148, v232
	v_fmac_f32_e32 v38, v148, v233
	v_fmac_f32_e32 v23, v149, v232
	v_fmac_f32_e32 v39, v149, v233
	v_fmac_f32_e32 v24, v150, v232
	v_fmac_f32_e32 v40, v150, v233
	v_fmac_f32_e32 v25, v151, v232
	v_fmac_f32_e32 v41, v151, v233
	v_mul_f32_e32 v232, v103, v206
	v_mul_f32_e32 v233, v103, v207
	v_fmac_f32_e32 v10, v152, v232
	v_fmac_f32_e32 v26, v152, v233
	v_fmac_f32_e32 v11, v153, v232
	v_fmac_f32_e32 v27, v153, v233
	v_fmac_f32_e32 v12, v154, v232
	v_fmac_f32_e32 v28, v154, v233
	v_fmac_f32_e32 v13, v155, v232
	v_fmac_f32_e32 v29, v155, v233
	v_fmac_f32_e32 v14, v156, v232
	v_fmac_f32_e32 v30, v156, v233
	v_fmac_f32_e32 v15, v157, v232
	v_fmac_f32_e32 v31, v157, v233
	v_fmac_f32_e32 v16, v158, v232
	v_fmac_f32_e32 v32, v158, v233
	v_fmac_f32_e32 v17, v159, v232
	v_fmac_f32_e32 v33, v159, v233
	v_fmac_f32_e32 v18, v160, v232
	v_fmac_f32_e32 v34, v160, v233
	v_fmac_f32_e32 v19, v161, v232
	v_fmac_f32_e32 v35, v161, v233
	v_fmac_f32_e32 v20, v162, v232
	v_fmac_f32_e32 v36, v162, v233
	v_fmac_f32_e32 v21, v163, v232
	v_fmac_f32_e32 v37, v163, v233
	v_fmac_f32_e32 v22, v164, v232
	v_fmac_f32_e32 v38, v164, v233
	v_fmac_f32_e32 v23, v165, v232
	v_fmac_f32_e32 v39, v165, v233
	v_fmac_f32_e32 v24, v166, v232
	v_fmac_f32_e32 v40, v166, v233
	v_fmac_f32_e32 v25, v167, v232
	v_fmac_f32_e32 v41, v167, v233
	ds_read_b128 v[104:107], v63 offset:768
	ds_read_b128 v[108:111], v63 offset:784
	ds_read_b128 v[112:115], v63 offset:800
	ds_read_b128 v[116:119], v63 offset:816
	ds_read_b128 v[120:123], v63 offset:832
	ds_read_b128 v[124:127], v63 offset:848
	ds_read_b128 v[128:131], v63 offset:864
	ds_read_b128 v[132:135], v63 offset:880
	ds_read_b128 v[136:139], v63 offset:896
	ds_read_b128 v[140:143], v63 offset:912
	ds_read_b128 v[144:147], v63 offset:928
	ds_read_b128 v[148:151], v63 offset:944
	ds_read_b128 v[152:155], v63 offset:960
	ds_read_b128 v[156:159], v63 offset:976
	ds_read_b128 v[160:163], v63 offset:992
	ds_read_b128 v[164:167], v63 offset:1008
	ds_read_b128 v[100:103], v63 offset:1072
	s_waitcnt lgkmcnt(0)
	v_mul_f32_e32 v232, v100, v208
	v_mul_f32_e32 v233, v100, v209
	v_fmac_f32_e32 v10, v104, v232
	v_fmac_f32_e32 v26, v104, v233
	v_fmac_f32_e32 v11, v105, v232
	v_fmac_f32_e32 v27, v105, v233
	v_fmac_f32_e32 v12, v106, v232
	v_fmac_f32_e32 v28, v106, v233
	v_fmac_f32_e32 v13, v107, v232
	v_fmac_f32_e32 v29, v107, v233
	v_fmac_f32_e32 v14, v108, v232
	v_fmac_f32_e32 v30, v108, v233
	v_fmac_f32_e32 v15, v109, v232
	v_fmac_f32_e32 v31, v109, v233
	v_fmac_f32_e32 v16, v110, v232
	v_fmac_f32_e32 v32, v110, v233
	v_fmac_f32_e32 v17, v111, v232
	v_fmac_f32_e32 v33, v111, v233
	v_fmac_f32_e32 v18, v112, v232
	v_fmac_f32_e32 v34, v112, v233
	v_fmac_f32_e32 v19, v113, v232
	v_fmac_f32_e32 v35, v113, v233
	v_fmac_f32_e32 v20, v114, v232
	v_fmac_f32_e32 v36, v114, v233
	v_fmac_f32_e32 v21, v115, v232
	v_fmac_f32_e32 v37, v115, v233
	v_fmac_f32_e32 v22, v116, v232
	v_fmac_f32_e32 v38, v116, v233
	v_fmac_f32_e32 v23, v117, v232
	v_fmac_f32_e32 v39, v117, v233
	v_fmac_f32_e32 v24, v118, v232
	v_fmac_f32_e32 v40, v118, v233
	v_fmac_f32_e32 v25, v119, v232
	v_fmac_f32_e32 v41, v119, v233
	v_mul_f32_e32 v232, v101, v210
	v_mul_f32_e32 v233, v101, v211
	v_fmac_f32_e32 v10, v120, v232
	v_fmac_f32_e32 v26, v120, v233
	v_fmac_f32_e32 v11, v121, v232
	v_fmac_f32_e32 v27, v121, v233
	v_fmac_f32_e32 v12, v122, v232
	v_fmac_f32_e32 v28, v122, v233
	v_fmac_f32_e32 v13, v123, v232
	v_fmac_f32_e32 v29, v123, v233
	v_fmac_f32_e32 v14, v124, v232
	v_fmac_f32_e32 v30, v124, v233
	v_fmac_f32_e32 v15, v125, v232
	v_fmac_f32_e32 v31, v125, v233
	v_fmac_f32_e32 v16, v126, v232
	v_fmac_f32_e32 v32, v126, v233
	v_fmac_f32_e32 v17, v127, v232
	v_fmac_f32_e32 v33, v127, v233
	v_fmac_f32_e32 v18, v128, v232
	v_fmac_f32_e32 v34, v128, v233
	v_fmac_f32_e32 v19, v129, v232
	v_fmac_f32_e32 v35, v129, v233
	v_fmac_f32_e32 v20, v130, v232
	v_fmac_f32_e32 v36, v130, v233
	v_fmac_f32_e32 v21, v131, v232
	v_fmac_f32_e32 v37, v131, v233
	v_fmac_f32_e32 v22, v132, v232
	v_fmac_f32_e32 v38, v132, v233
	v_fmac_f32_e32 v23, v133, v232
	v_fmac_f32_e32 v39, v133, v233
	v_fmac_f32_e32 v24, v134, v232
	v_fmac_f32_e32 v40, v134, v233
	v_fmac_f32_e32 v25, v135, v232
	v_fmac_f32_e32 v41, v135, v233
	v_mul_f32_e32 v232, v102, v212
	v_mul_f32_e32 v233, v102, v213
	v_fmac_f32_e32 v10, v136, v232
	v_fmac_f32_e32 v26, v136, v233
	v_fmac_f32_e32 v11, v137, v232
	v_fmac_f32_e32 v27, v137, v233
	v_fmac_f32_e32 v12, v138, v232
	v_fmac_f32_e32 v28, v138, v233
	v_fmac_f32_e32 v13, v139, v232
	v_fmac_f32_e32 v29, v139, v233
	v_fmac_f32_e32 v14, v140, v232
	v_fmac_f32_e32 v30, v140, v233
	v_fmac_f32_e32 v15, v141, v232
	v_fmac_f32_e32 v31, v141, v233
	v_fmac_f32_e32 v16, v142, v232
	v_fmac_f32_e32 v32, v142, v233
	v_fmac_f32_e32 v17, v143, v232
	v_fmac_f32_e32 v33, v143, v233
	v_fmac_f32_e32 v18, v144, v232
	v_fmac_f32_e32 v34, v144, v233
	v_fmac_f32_e32 v19, v145, v232
	v_fmac_f32_e32 v35, v145, v233
	v_fmac_f32_e32 v20, v146, v232
	v_fmac_f32_e32 v36, v146, v233
	v_fmac_f32_e32 v21, v147, v232
	v_fmac_f32_e32 v37, v147, v233
	v_fmac_f32_e32 v22, v148, v232
	v_fmac_f32_e32 v38, v148, v233
	v_fmac_f32_e32 v23, v149, v232
	v_fmac_f32_e32 v39, v149, v233
	v_fmac_f32_e32 v24, v150, v232
	v_fmac_f32_e32 v40, v150, v233
	v_fmac_f32_e32 v25, v151, v232
	v_fmac_f32_e32 v41, v151, v233
	v_mul_f32_e32 v232, v103, v214
	v_mul_f32_e32 v233, v103, v215
	v_fmac_f32_e32 v10, v152, v232
	v_fmac_f32_e32 v26, v152, v233
	v_fmac_f32_e32 v11, v153, v232
	v_fmac_f32_e32 v27, v153, v233
	v_fmac_f32_e32 v12, v154, v232
	v_fmac_f32_e32 v28, v154, v233
	v_fmac_f32_e32 v13, v155, v232
	v_fmac_f32_e32 v29, v155, v233
	v_fmac_f32_e32 v14, v156, v232
	v_fmac_f32_e32 v30, v156, v233
	v_fmac_f32_e32 v15, v157, v232
	v_fmac_f32_e32 v31, v157, v233
	v_fmac_f32_e32 v16, v158, v232
	v_fmac_f32_e32 v32, v158, v233
	v_fmac_f32_e32 v17, v159, v232
	v_fmac_f32_e32 v33, v159, v233
	v_fmac_f32_e32 v18, v160, v232
	v_fmac_f32_e32 v34, v160, v233
	v_fmac_f32_e32 v19, v161, v232
	v_fmac_f32_e32 v35, v161, v233
	v_fmac_f32_e32 v20, v162, v232
	v_fmac_f32_e32 v36, v162, v233
	v_fmac_f32_e32 v21, v163, v232
	v_fmac_f32_e32 v37, v163, v233
	v_fmac_f32_e32 v22, v164, v232
	v_fmac_f32_e32 v38, v164, v233
	v_fmac_f32_e32 v23, v165, v232
	v_fmac_f32_e32 v39, v165, v233
	v_fmac_f32_e32 v24, v166, v232
	v_fmac_f32_e32 v40, v166, v233
	v_fmac_f32_e32 v25, v167, v232
	v_fmac_f32_e32 v41, v167, v233
	s_waitcnt lgkmcnt(0)
	s_barrier
	s_lshl_b32 s30, s94, 13
	v_lshl_add_u32 v58, v1, 7, s30
	ds_write_b128 v58, v[10:13]
	ds_write_b128 v58, v[14:17] offset:16
	ds_write_b128 v58, v[18:21] offset:32
	ds_write_b128 v58, v[22:25] offset:48
	ds_write_b128 v58, v[26:29] offset:64
	ds_write_b128 v58, v[30:33] offset:80
	ds_write_b128 v58, v[34:37] offset:96
	ds_write_b128 v58, v[38:41] offset:112
	s_waitcnt lgkmcnt(0)
	s_barrier
	s_lshl_b32 s30, s94, 10
	v_lshl_add_u32 v58, v1, 4, s30
	ds_read_b128 v[192:195], v58
	ds_read_b128 v[196:199], v58 offset:8192
	ds_read_b128 v[200:203], v58 offset:16384
	ds_read_b128 v[204:207], v58 offset:24576
	ds_read_b128 v[208:211], v58 offset:32768
	ds_read_b128 v[212:215], v58 offset:40960
	ds_read_b128 v[216:219], v58 offset:49152
	ds_read_b128 v[220:223], v58 offset:57344
	s_waitcnt lgkmcnt(0)
	v_pk_add_f32 v[192:193], v[192:193], v[196:197]
	v_pk_add_f32 v[194:195], v[194:195], v[198:199]
	v_pk_add_f32 v[192:193], v[192:193], v[200:201]
	v_pk_add_f32 v[194:195], v[194:195], v[202:203]
	v_pk_add_f32 v[192:193], v[192:193], v[204:205]
	v_pk_add_f32 v[194:195], v[194:195], v[206:207]
	v_pk_add_f32 v[192:193], v[192:193], v[208:209]
	v_pk_add_f32 v[194:195], v[194:195], v[210:211]
	v_pk_add_f32 v[192:193], v[192:193], v[212:213]
	v_pk_add_f32 v[194:195], v[194:195], v[214:215]
	v_pk_add_f32 v[192:193], v[192:193], v[216:217]
	v_pk_add_f32 v[194:195], v[194:195], v[218:219]
	v_pk_add_f32 v[192:193], v[192:193], v[220:221]
	v_pk_add_f32 v[194:195], v[194:195], v[222:223]
	s_lshl_b32 s30, s18, 7
	s_lshl_b32 s31, s94, 4
	s_add_i32 s30, s30, s31
	v_add_u32_e32 v8, s30, v2
	v_lshlrev_b32_e32 v8, 11, v8
	v_lshl_add_u32 v8, v3, 3, v8
	s_lshl_b32 s30, s1, 7
	s_lshl_b32 s31, s9, 4
	s_add_i32 s30, s30, s31
	s_lshl_b32 s30, s30, 1
	s_add_u32 s34, s64, s30
	s_addc_u32 s35, s65, 0
	v_cvt_pk_bf16_f32 v6, v192, v193
	v_cvt_pk_bf16_f32 v7, v194, v195
	s_nop 1
	global_store_dwordx2 v8, v[6:7], s[34:35]
	s_waitcnt vmcnt(0) lgkmcnt(0)
	s_barrier
	s_branch .LBB0_70
